# MLA attention loop: s_setprio 1 around QK/PV MFMA blocks, 0 for softmax; counted LDS waits + 2-step K prefetch; K tile 4-bit swizzle
# speedup vs baseline: 1.0081x; 1.0081x over previous
; #define LAS __attribute__((address_space(3)))
; __device__ __forceinline__ void attn_core_pair(f32x16 (&o)[4], const bf16_t* __restrict__ Qb, const bf16_t* __restrict__ Kh, const bf16_t* __restrict__ Vh, const int seq, const float C, const float thr_raw, char* lds) {
;   const int tid = threadIdx.x, wid = tid >> 6, lane = tid & 63, r32 = lane & 31, hi = lane >> 5, rb = wid & 3, role = wid >> 2;
;   char* K_lds = lds + PR_K; char* V_lds = lds + PR_V; char* P_l = lds + PR_P + rb * 4096 + lane * 16;
;   float* ma = (float*)(lds + PR_MA); float* m_l = ma + rb * 32; float* l_l = ma + 128 + rb * 32; unsigned* fl_l = (unsigned*)(ma + 512);
; #pragma unroll
;   for (int d = 0; d < 4; ++d) o[d] = f32x16{};
;   bf16x8 qr[8];
;   { const bf16_t* Qw = Qb + (long)(rb * 32 + r32) * 1024 + hi * 8;
; #pragma unroll
;     for (int d0 = 0; d0 < 8; ++d0) { qr[d0] = *reinterpret_cast<const bf16x8*>(Qw + d0 * 16); asm volatile("" : "+v"(qr[d0])); } }
;   const int sr = tid >> 4, sc = (tid & 15) * 8, vst0 = v_st(sr, sc), vst1 = v_st(32 + sr, sc);
;   const int vb0 = (int)(uintptr_t)(LAS char*)V_lds + role * SHM_V + v_rd_base(lane);
;   bf16x8 ks0, ks1, va0, va1, vb_0, vb_1;
; __global__ void __launch_bounds__(512, 2) fwd_megakernel(const Params p) {
;     ...
;     const int wid = tid >> 6, lane = tid & 63, r32 = lane & 31, hi = lane >> 5;
;     const float LOG2E = 1.4426950408889634f;
;     ...
;     for (int it = 0; bid + (it >> 2) * G < 256 * (1 + ((DUPMASK >> 3) & 1)); ++it) {
;       const int pass = it & 3, hb = pass >> 1, u = (bid + (it >> 2) * G) & 255, x = u & 7, y = u >> 3, qb = y & 7, bh = (y >> 3) * 8 + x, b = bh >> 2, h = bh & 3;
;       const size_t rowq = (size_t)b * SEQ + qb * 256, rowk = (size_t)b * SEQ;
;       const int qsel = (pass & 1) ? 0 : 128;
;       const bf16_t* dq = (const bf16_t*)(ws + O_DQ) + (rowq + hb * 128) * 1024 + h * 256 + qsel; const bf16_t* dk = (const bf16_t*)(ws + O_DK) + rowk * 1024 + h * 256 + qsel;
;       const bf16_t* dv = (const bf16_t*)(ws + O_DV) + rowk * 1024 + h * 256;
;       f32x4* sl = (f32x4*)(ws + O_SCR) + ((size_t)(u * 16 + (hb * 2 + (wid >> 2)) * 4 + (wid & 3)) * 1024 + lane);
;       const float lam = ssb[SS_LAM]; const float C = 0.08838834764831845f * LOG2E, thr = 8.f / 0.08838834764831845f;
;       f32x16 o[4];
.LBB0_369:
	s_or_b64 exec, exec, s[0:1]
	s_cmp_lt_i32 s76, 4
	s_cselect_b64 s[0:1], -1, 0
	s_cmp_gt_i32 s77, 3
	s_cselect_b64 s[2:3], -1, 0
	s_and_b64 s[0:1], s[0:1], s[2:3]
	s_andn2_b64 vcc, exec, s[0:1]
	v_bfe_u32 v154, v187, 5, 1
	v_lshrrev_b32_e32 v193, 6, v187
	s_waitcnt lgkmcnt(0)
	s_barrier
	s_cbranch_vccnz .LBB0_439
	v_and_b32_e32 v194, 63, v187
	s_cmpk_lt_i32 s14, 0x100
	s_cselect_b64 s[0:1], -1, 0
	s_movk_i32 s6, 0xff
	s_cmpk_gt_i32 s14, 0xff
	v_lshlrev_b32_e32 v156, 4, v194
	v_lshlrev_b32_e32 v155, 8, v152
	v_cmp_gt_u32_e64 s[2:3], 32, v194
	s_cbranch_scc1 .LBB0_411
	s_add_i32 s4, 0, 0x24000
	s_add_u32 s15, s74, 0xcb00000
	s_addc_u32 s33, s75, 0
	s_add_u32 s42, s74, 0xeb00000
	s_addc_u32 s43, s75, 0
	v_and_b32_e32 v6, 48, v153
	v_lshrrev_b32_e32 v8, 3, v187
	s_add_u32 s44, s74, 0x10b00000
	v_and_or_b32 v6, v8, 8, v6
	s_addc_u32 s45, s75, 0
	v_and_b32_e32 v4, 0x78, v192
	v_lshrrev_b32_e32 v8, 5, v187
	v_lshrrev_b32_e32 v6, 1, v6
	v_bfe_u32 v9, v192, 5, 2
	v_bfe_u32 v10, v187, 4, 2
	s_add_u32 s18, s74, 0x7100000
	v_or_b32_e32 v6, v6, v9
	v_and_or_b32 v8, v8, 4, v10
	v_lshlrev_b32_e32 v11, 1, v4
	s_addc_u32 s19, s75, 0
	v_lshlrev_b32_e32 v6, 9, v6
	v_lshlrev_b32_e32 v8, 6, v8
	v_and_b32_e32 v10, 48, v11
	v_add_u32_e32 v14, 32, v153
	s_add_u32 s20, s74, 0x70d0000
	v_or3_b32 v196, v6, v8, v10
	v_and_b32_e32 v6, 0x70, v14
	v_lshlrev_b32_e32 v12, 1, v14
	v_bfe_u32 v3, v187, 6, 2
	s_addc_u32 s21, s75, 0
	s_add_i32 s5, 0, 0x20000
	v_and_or_b32 v6, v12, 8, v6
	v_lshl_add_u32 v5, v3, 12, s5
	s_add_i32 s5, 0, 0x24200
	v_lshlrev_b32_e32 v7, 7, v3
	v_lshrrev_b32_e32 v6, 1, v6
	v_lshlrev_b32_e32 v1, 2, v152
	v_add_u32_e32 v195, s5, v7
	v_or_b32_e32 v6, v6, v9
	v_lshlrev_b32_e32 v0, 10, v152
	v_lshrrev_b32_e32 v157, 8, v187
	v_lshlrev_b32_e32 v6, 9, v6
	v_and_b32_e32 v17, 0xc0, v156
	v_lshlrev_b32_e32 v20, 1, v187
	s_add_i32 s8, 0, 0x24800
	v_add3_u32 v201, s4, v1, v7
	v_add_u32_e32 v203, v195, v1
	v_lshlrev_b32_e32 v1, 4, v187
	v_lshl_or_b32 v0, v3, 15, v0
	v_or3_b32 v197, v6, v8, v10
	v_lshlrev_b32_e32 v15, 14, v157
	v_lshlrev_b32_e32 v10, 10, v14
	v_lshlrev_b32_e32 v16, 8, v153
	v_and_b32_e32 v18, 0xf0, v187
	v_lshlrev_b32_e32 v14, 8, v14
	v_lshl_add_u32 v200, v3, 2, s8
	v_and_or_b32 v3, v20, 32, v17
	v_lshlrev_b32_e32 v202, 4, v154
	v_and_b32_e32 v17, 0xf0, v1
	s_movk_i32 s4, 0x60
	s_add_i32 s9, 0, 0x8000
	s_movk_i32 s5, 0x70
	v_bitop3_b32 v198, v11, v16, v18 bitop3:0xde
	v_bitop3_b32 v199, v11, v14, v18 bitop3:0xde
	v_and_b32_e32 v11, 0x118, v192
	v_bitop3_b32 v28, v202, v17, s4 bitop3:0x36
	s_movk_i32 s4, 0x80
	v_add_u32_e32 v40, s9, v15
	v_xor_b32_e32 v1, v202, v17
	v_bitop3_b32 v29, v202, v17, s4 bitop3:0x36
	s_movk_i32 s4, 0xa0
	v_add3_u32 v204, v40, v11, v3
	v_add_u32_e32 v3, 0, v15
	s_movk_i32 s7, 0xc0
	v_lshlrev_b32_e32 v6, 10, v153
	v_bitop3_b32 v30, v202, v17, s4 bitop3:0x36
	s_movk_i32 s4, 0xe0
	v_add_u32_e32 v32, 0, v1
	v_add_u32_e32 v205, v3, v1
	v_and_b32_e32 v1, 15, v187
	v_mov_b32_e32 v159, 0
	v_or_b32_e32 v8, v6, v4
	v_or_b32_e32 v14, 0x10000, v6
	v_bitop3_b32 v21, v202, v17, 32 bitop3:0x36
	v_bitop3_b32 v25, v202, v17, 64 bitop3:0x36
	v_bitop3_b32 v31, v202, v17, s7 bitop3:0x36
	v_bitop3_b32 v17, v202, v17, s4 bitop3:0x36
	v_or_b32_e32 v20, 0x20000, v6
	v_add_u32_e32 v24, 0x28000, v6
	v_lshlrev_b32_e32 v1, 4, v1
	v_lshlrev_b32_e32 v2, 3, v154
	v_mov_b32_e32 v9, v159
	v_or_b32_e32 v12, v10, v4
	v_mov_b32_e32 v13, v159
	v_add_u32_e32 v16, 0x18000, v8
	v_or_b32_e32 v18, v14, v4
	v_mov_b32_e32 v19, v159
	s_add_i32 s8, 0, 0x24400
	v_add_u32_e32 v33, 0, v21
	v_add_u32_e32 v34, 0, v25
	v_add_u32_e32 v35, 0, v28
	v_add_u32_e32 v36, 0, v29
	v_add_u32_e32 v37, 0, v30
	v_add_u32_e32 v38, 0, v31
	v_add_u32_e32 v39, 0, v17
	v_or_b32_e32 v22, v20, v4
	v_mov_b32_e32 v23, v159
	v_or_b32_e32 v26, v24, v4
	v_mov_b32_e32 v27, v159
	v_lshl_or_b32 v158, v153, 11, v1
	s_mov_b32 s17, 0
	v_cmp_eq_u32_e64 s[4:5], 0, v194
	v_cmp_lt_u32_e64 s[6:7], s6, v187
	v_add_u32_e32 v206, v3, v21
	v_add_u32_e32 v207, v3, v25
	v_add_u32_e32 v208, v3, v28
	v_add_u32_e32 v209, v3, v29
	v_add_u32_e32 v210, v3, v30
	v_add_u32_e32 v211, v3, v31
	v_add_u32_e32 v212, v3, v17
	v_lshlrev_b32_e32 v213, 9, v157
	v_lshlrev_b32_e32 v214, 4, v157
	v_add3_u32 v215, s8, v7, v202
	v_cmp_eq_u32_e64 s[8:9], 1, v157
	v_cmp_ne_u32_e64 s[10:11], 1, v157
	v_lshl_add_u64 v[160:161], s[74:75], 0, v[158:159]
	v_lshlrev_b32_e32 v158, 1, v0
	v_lshlrev_b32_e32 v162, 1, v2
	v_lshlrev_b64 v[164:165], 1, v[8:9]
	v_lshlrev_b64 v[166:167], 1, v[12:13]
	v_lshlrev_b32_e32 v168, 1, v6
	v_lshlrev_b32_e32 v170, 1, v4
	v_lshlrev_b32_e32 v172, 1, v10
	s_mov_b32 s46, 0x30000
	v_lshlrev_b32_e32 v174, 1, v14
	v_lshlrev_b32_e32 v216, 1, v16
	v_lshlrev_b64 v[176:177], 1, v[18:19]
	v_add_u32_e32 v217, v32, v155
	v_add_u32_e32 v218, v33, v155
	v_add_u32_e32 v219, v34, v155
	v_add_u32_e32 v220, v35, v155
	v_add_u32_e32 v221, v36, v155
	v_add_u32_e32 v222, v37, v155
	v_add_u32_e32 v223, v38, v155
	v_add_u32_e32 v224, v39, v155
	s_mov_b32 s47, 0x42b504f3
	s_add_i32 s48, 0, 0x14000
	s_mov_b64 s[22:23], 0x2000
	s_movk_i32 s49, 0x2000
	s_movk_i32 s50, 0x1000
	s_movk_i32 s51, 0x3000
	v_add_u32_e32 v225, v5, v156
	v_mov_b32_e32 v226, 0xf149f2ca
	s_add_i32 s52, 0, 0x10000
	v_lshlrev_b64 v[178:179], 1, v[22:23]
	v_lshlrev_b64 v[180:181], 1, v[26:27]
	v_lshlrev_b32_e32 v182, 1, v20
	v_lshlrev_b32_e32 v184, 1, v24
	s_mov_b32 s55, s14
	s_mov_b32 s53, 0
	s_branch .LBB0_373

; template <int NQK, int LDQ, int LDQR> ...
;   const int tid = threadIdx.x, wid = tid >> 6, lane = tid & 63, r32 = lane & 31, hi = lane >> 5, grp = wid >> 2;
;   char* V_lds = lds + R_V; char* K_lds = lds + R_K; char* KR_lds = lds + R_KR;
;   float* ws = (float*)(lds + R_WS) + wid * 64; float* li_l = ws; float* al_l = ws + 32;
;   float m_reg = -1e30f, l_reg = 0;
; #pragma unroll
;   for (int d = 0; d < 4; ++d) o[d] = f32x16{};
;   bf16x8 qr[8]; char* qrl = lds + R_QR + wid * 4096 - 4096;
;   { const bf16_t* Qw = Qb + (long)(wid * 32 + r32) * LDQ + hi * 8;
; #pragma unroll
;     for (int d0 = 0; d0 < 8; ++d0) { qr[d0] = *reinterpret_cast<const bf16x8*>(Qw + d0 * 16); asm volatile("" : "+v"(qr[d0])); }
;     if constexpr (NQK == 12) { const bf16_t* Qw2 = Qrb + (long)(wid * 32 + r32) * LDQR + hi * 8;
; #pragma unroll
;       for (int d0 = 0; d0 < 4; ++d0) *reinterpret_cast<bf16x8*>(qrl + 4096 + KRSWZ(r32, d0 * 2 + hi)) = *reinterpret_cast<const bf16x8*>(Qw2 + d0 * 16); } }
;   const int sr = tid >> 4, sc = (tid & 15) * 8, vst0 = v_st(sr, sc), vst1 = v_st(32 + sr, sc);
;   const int krr = tid >> 3, krc = tid & 7;
;   const int vb0 = (int)(uintptr_t)(LAS char*)V_lds + v_rd_base(lane);
;   bf16x8 vs0, vs1, ks0, ks1, kr;
;     ...
;   f32x16 p0, p1; float mn, al; bf16x8 pa0, pa1, pa2, pa3; const int NT = seq / KVBLK;
;   SLOAD1(0); SWRITE1(0, 0); __syncthreads();
;   if (1 < NT) SLOAD1(KVBLK);
;   int vprev = 2, vcur = 0, vnext = 1;
; __global__ void __launch_bounds__(512, 2) fwd_megakernel(const Params p) {
;     ...
;     for (int uu = bid; uu < 512 * (1 + ((DUPMASK >> 3) & 1)); uu += G) {
;       const int u = uu & 511, x = u & 7, y = u >> 3, qb = y & 7, bh = (y >> 3) * 8 + x, b = bh >> 3, h = bh & 7;
;       const size_t rowq = (size_t)b * SEQ + qb * 256, rowk = (size_t)b * SEQ;
;       const float sc = 0.07216878364870322f;
;       f32x16 o[4];
;       at::attn_core_rot<12, 1024, 512>(o, (const bf16_t*)(ws + O_QN) + rowq * 1024 + h * 128, (const bf16_t*)(ws + O_QR) + rowq * 512 + h * 64,
;                                    (const bf16_t*)(ws + O_KN) + rowk * 1024 + h * 128, (const bf16_t*)(ws + O_KR) + rowk * 64, (const bf16_t*)(ws + O_VM) + rowk * 1024 + h * 128,
;                                    SEQ, sc * LOG2E, 8.f / sc, (char*)shm);
;       at::store_o_bf16_lds(o, (bf16_t*)(ws + O_ATT) + rowq * 2048 + h * 128, 2048, (char*)shm + at::R_QR + (tid >> 6) * 4096);
.LBB0_418:
	s_cmpk_gt_i32 s14, 0x1ff
	s_barrier
	s_cbranch_scc1 .LBB0_439
	v_lshrrev_b32_e32 v3, 1, v187
	v_bfe_u32 v2, v187, 1, 3
	v_bitop3_b32 v4, v154, v3, 7 bitop3:0x78
	v_lshlrev_b32_e32 v177, 4, v4
	v_bitop3_b32 v4, v154, v2, 2 bitop3:0x36
	v_lshlrev_b32_e32 v178, 4, v4
	v_bitop3_b32 v4, v154, v2, 4 bitop3:0x36
	v_bitop3_b32 v2, v154, v2, 6 bitop3:0x36
	v_lshlrev_b32_e32 v180, 4, v2
	v_and_b32_e32 v2, 48, v153
	v_lshrrev_b32_e32 v5, 3, v187
	s_add_u32 s15, s74, 0x13300000
	v_and_or_b32 v2, v5, 8, v2
	s_addc_u32 s20, s75, 0
	v_lshlrev_b32_e32 v179, 4, v4
	v_and_b32_e32 v4, 0x78, v192
	v_lshrrev_b32_e32 v6, 5, v187
	v_lshrrev_b32_e32 v2, 1, v2
	v_bfe_u32 v7, v192, 5, 2
	v_bfe_u32 v8, v187, 4, 2
	s_add_u32 s21, s74, 0x17300000
	v_or_b32_e32 v2, v2, v7
	v_and_or_b32 v6, v6, 4, v8
	v_lshlrev_b32_e32 v8, 1, v4
	s_addc_u32 s22, s75, 0
	v_lshlrev_b32_e32 v2, 9, v2
	v_lshlrev_b32_e32 v6, 6, v6
	v_and_b32_e32 v9, 48, v8
	v_add_u32_e32 v10, 32, v153
	s_add_u32 s23, s74, 0x15300000
	v_or3_b32 v181, v2, v6, v9
	v_and_b32_e32 v2, 0x70, v10
	v_lshlrev_b32_e32 v11, 1, v10
	s_addc_u32 s28, s75, 0
	v_and_or_b32 v2, v11, 8, v2
	s_add_u32 s29, s74, 0xc900000
	v_lshrrev_b32_e32 v2, 1, v2
	s_addc_u32 s30, s75, 0
	v_or_b32_e32 v2, v2, v7
	s_add_u32 s31, s74, 0x18300000
	v_lshlrev_b32_e32 v2, 9, v2
	s_addc_u32 s33, s75, 0
	v_and_b32_e32 v0, 0x3c0, v187
	s_add_i32 s0, 0, 0x18000
	v_or3_b32 v182, v2, v6, v9
	v_lshlrev_b32_e32 v7, 4, v187
	v_lshlrev_b32_e32 v9, 1, v187
	v_lshl_add_u32 v174, v0, 2, s0
	s_add_i32 s0, 0, 0x18800
	v_and_b32_e32 v2, 0xc0, v7
	v_and_b32_e32 v6, 32, v9
	v_and_b32_e32 v11, 0x118, v192
	v_lshl_add_u32 v175, v193, 12, s0
	s_movk_i32 s0, 0x70
	v_or3_b32 v11, v6, v2, v11
	v_lshl_or_b32 v2, v153, 10, v4
	v_lshl_or_b32 v4, v10, 10, v4
	v_and_b32_e32 v6, 56, v192
	v_lshlrev_b32_e32 v12, 8, v153
	v_and_b32_e32 v13, 0xf0, v187
	v_lshlrev_b32_e32 v10, 8, v10
	v_lshl_or_b32 v6, v5, 6, v6
	v_bitop3_b32 v184, v8, v12, v13 bitop3:0xde
	v_bitop3_b32 v185, v8, v10, v13 bitop3:0xde
	v_lshlrev_b32_e32 v5, 7, v5
	v_bitop3_b32 v8, v7, s0, v187 bitop3:0x48
	s_add_i32 s2, 0, 0x14000
	v_and_b32_e32 v13, 0x300, v187
	s_movk_i32 s6, 0x100
	v_lshlrev_b32_e32 v188, 4, v154
	v_add3_u32 v186, s2, v8, v5
	v_cmp_eq_u32_e64 s[2:3], s6, v13
	v_and_b32_e32 v13, 0xf0, v7
	v_xor_b32_e32 v189, v188, v13
	s_movk_i32 s0, 0x60
	v_bitop3_b32 v195, v188, v13, s0 bitop3:0x36
	s_movk_i32 s0, 0x80
	v_bitop3_b32 v196, v188, v13, s0 bitop3:0x36
	s_movk_i32 s0, 0xa0
	v_lshl_or_b32 v1, v193, 5, v152
	v_bitop3_b32 v197, v188, v13, s0 bitop3:0x36
	s_movk_i32 s0, 0xe0
	s_waitcnt vmcnt(0)
	v_lshlrev_b32_e32 v148, 11, v1
	v_lshlrev_b32_e32 v156, 10, v1
	v_lshlrev_b32_e32 v1, 7, v152
	v_bitop3_b32 v199, v188, v13, s0 bitop3:0x36
	s_add_i32 s0, 0, 0x4000
	v_and_b32_e32 v7, 62, v9
	v_lshlrev_b32_e32 v9, 1, v2
	v_mov_b32_e32 v151, 0
	v_add_u32_e32 v176, v175, v1
	v_or_b32_e32 v200, v177, v1
	v_or_b32_e32 v201, v178, v1
	v_or_b32_e32 v202, v179, v1
	v_or_b32_e32 v203, v180, v1
	v_add_u32_e32 v204, s0, v11
	v_bfe_u32 v1, v187, 3, 3
	s_movk_i32 s0, 0x1e0
	v_add_u32_e32 v150, 0x50000, v9
	v_and_or_b32 v3, v3, s0, v1
	v_lshl_add_u64 v[158:159], s[74:75], 0, v[150:151]
	v_or_b32_e32 v150, 0x40000, v9
	v_mov_b32_e32 v9, 0x4000
	v_lshlrev_b32_e32 v14, 11, v3
	v_and_b32_e32 v3, 7, v187
	v_lshl_add_u64 v[160:161], s[74:75], 0, v[150:151]
	v_lshl_or_b32 v150, v6, 1, v9
	s_mov_b64 s[8:9], 0xc900000
	v_lshlrev_b32_e32 v0, 3, v154
	s_movk_i32 s4, 0xc0
	v_add_u32_e32 v8, 0x1000, v6
	v_add_u32_e32 v10, 0x18000, v2
	v_or_b32_e32 v12, 0x10000, v2
	s_add_u32 s40, s74, 0x1a300000
	v_lshlrev_b32_e32 v16, 3, v3
	v_lshl_add_u32 v3, v3, 4, v175
	v_lshlrev_b32_e32 v1, 7, v1
	v_add_u32_e32 v7, v175, v7
	v_and_b32_e32 v5, 0x200, v5
	v_lshl_add_u64 v[18:19], s[74:75], 0, v[150:151]
	s_mov_b32 s1, 0
	s_mov_b32 s38, 0x18000
	v_mov_b32_e32 v149, v151
	v_mov_b32_e32 v157, v151
	v_add_u32_e32 v183, 0, v11
	s_mov_b32 s39, 0x10000
	v_bitop3_b32 v190, v188, v13, 32 bitop3:0x36
	v_bitop3_b32 v191, v188, v13, 64 bitop3:0x36
	v_bitop3_b32 v198, v188, v13, s4 bitop3:0x36
	v_cmp_gt_u32_e64 s[4:5], 32, v194
	v_lshl_add_u32 v194, v152, 2, v174
	v_cmp_gt_u32_e64 s[6:7], s6, v187
	s_addc_u32 s41, s75, 0
	s_lshl_b32 s42, s14, 5
	s_lshl_b32 s43, s78, 5
	v_lshl_add_u64 v[162:163], v[18:19], 0, s[8:9]
	s_mov_b32 s44, 0x42ddb3d8
	s_mov_b64 s[10:11], 0x2000
	v_lshlrev_b32_e32 v150, 1, v14
	v_lshlrev_b32_e32 v164, 1, v16
	v_add_u32_e32 v205, v7, v5
	v_add_u32_e32 v206, v3, v1
	s_mov_b32 s45, 0x8000
	v_lshlrev_b32_e32 v166, 1, v0
	v_lshlrev_b32_e32 v207, 1, v2
	v_lshlrev_b32_e32 v208, 1, v4
	v_lshlrev_b32_e32 v209, 1, v6
	v_lshlrev_b32_e32 v210, 1, v8
	v_lshlrev_b32_e32 v211, 1, v10
	v_lshlrev_b32_e32 v212, 1, v12
	s_mov_b32 s46, s14
	s_mov_b32 s47, s14
	s_branch .LBB0_421

; #define SBAR() __builtin_amdgcn_sched_barrier(0)
; template <int NQK, int NREG>
; __device__ __forceinline__ void qkt(f32x16& p0, f32x16& p1, const char* Ks, const char* KRs, const bf16x8* qr, const char* qrl, int r32, int hi) {
;   p0 = f32x16{}; p1 = f32x16{};
; #pragma unroll
;   for (int d0 = 0; d0 < 8; ++d0) { const int cb = (d0 * 16 + hi * 8) * 2;
;     bf16x8 b0 = *reinterpret_cast<const bf16x8*>(Ks + KSWZ(r32, cb));
;     bf16x8 b1 = *reinterpret_cast<const bf16x8*>(Ks + KSWZ(32 + r32, cb));
;     bf16x8 qq; if (d0 < NREG) qq = qr[d0 < NREG ? d0 : 0]; else qq = *reinterpret_cast<const bf16x8*>(qrl + KRSWZ(r32, (d0 - 4) * 2 + hi));
;     p0 = __builtin_amdgcn_mfma_f32_32x32x16_bf16(b0, qq, p0, 0, 0, 0);
;     p1 = __builtin_amdgcn_mfma_f32_32x32x16_bf16(b1, qq, p1, 0, 0, 0); }
;   if constexpr (NQK == 12) {
; #pragma unroll
;     for (int d0 = 0; d0 < 4; ++d0) { const int ch = d0 * 2 + hi;
;       bf16x8 b0 = *reinterpret_cast<const bf16x8*>(KRs + KRSWZ(r32, ch));
;       bf16x8 b1 = *reinterpret_cast<const bf16x8*>(KRs + KRSWZ(32 + r32, ch));
;       const bf16x8 qq = *reinterpret_cast<const bf16x8*>(qrl + 4096 + KRSWZ(r32, ch));
;       p0 = __builtin_amdgcn_mfma_f32_32x32x16_bf16(b0, qq, p0, 0, 0, 0);
;       p1 = __builtin_amdgcn_mfma_f32_32x32x16_bf16(b1, qq, p1, 0, 0, 0); }
;   }
; }
; template <int D0> __device__ __forceinline__ void pv_one(f32x16& od, int vb, bf16x8 pa0, bf16x8 pa1, bf16x8 pa2, bf16x8 pa3) {
;   const s16x4 l0 = tr_read<v_rd_off(D0, 0, 0)>(vb), h0 = tr_read<v_rd_off(D0, 0, 1)>(vb), l1 = tr_read<v_rd_off(D0, 1, 0)>(vb), h1 = tr_read<v_rd_off(D0, 1, 1)>(vb);
;   const s16x4 l2 = tr_read<v_rd_off(D0, 2, 0)>(vb), h2 = tr_read<v_rd_off(D0, 2, 1)>(vb), l3 = tr_read<v_rd_off(D0, 3, 0)>(vb), h3 = tr_read<v_rd_off(D0, 3, 1)>(vb);
;   asm volatile("s_waitcnt lgkmcnt(0)" ::: "memory"); SBAR();
;     ...
;   od = __builtin_amdgcn_mfma_f32_32x32x16_bf16(pa0, PK(l0, h0), od, 0, 0, 0);
;   od = __builtin_amdgcn_mfma_f32_32x32x16_bf16(pa1, PK(l1, h1), od, 0, 0, 0);
;   od = __builtin_amdgcn_mfma_f32_32x32x16_bf16(pa2, PK(l2, h2), od, 0, 0, 0);
;   od = __builtin_amdgcn_mfma_f32_32x32x16_bf16(pa3, PK(l3, h3), od, 0, 0, 0);
;     ...
; }
.LBB0_422:
	s_setprio 1
	s_cmp_lg_u32 s16, 0
	s_mov_b32 s51, s50
	s_mov_b32 s50, s8
	s_cselect_b64 s[8:9], -1, 0
	s_and_b64 s[52:53], s[2:3], s[8:9]
	s_and_saveexec_b64 s[8:9], s[52:53]
	s_cbranch_execz .LBB0_424
	v_lshl_add_u32 v213, s18, 14, v183
	ds_read_b64_tr_b16 v[80:81], v213 offset:0
	ds_read_b64_tr_b16 v[82:83], v213 offset:0x800
	ds_read_b64_tr_b16 v[84:85], v213 offset:0x1000
	ds_read_b64_tr_b16 v[86:87], v213 offset:0x1800
	ds_read_b64_tr_b16 v[88:89], v213 offset:0x2000
	ds_read_b64_tr_b16 v[90:91], v213 offset:0x2800
	ds_read_b64_tr_b16 v[92:93], v213 offset:0x3000
	ds_read_b64_tr_b16 v[94:95], v213 offset:0x3800
	s_waitcnt lgkmcnt(6)
	v_mfma_f32_32x32x16_bf16 v[0:15], v[76:79], v[80:83], v[0:15]
	ds_read_b64_tr_b16 v[80:81], v213 offset:0x200
	ds_read_b64_tr_b16 v[82:83], v213 offset:0xa00
	s_waitcnt lgkmcnt(6)
	v_mfma_f32_32x32x16_bf16 v[0:15], v[72:75], v[84:87], v[0:15]
	ds_read_b64_tr_b16 v[84:85], v213 offset:0x1200
	ds_read_b64_tr_b16 v[86:87], v213 offset:0x1a00
	s_waitcnt lgkmcnt(6)
	v_mfma_f32_32x32x16_bf16 v[0:15], v[68:71], v[88:91], v[0:15]
	ds_read_b64_tr_b16 v[88:89], v213 offset:0x2200
	ds_read_b64_tr_b16 v[90:91], v213 offset:0x2a00
	ds_read_b64_tr_b16 v[214:215], v213 offset:0x3200
	ds_read_b64_tr_b16 v[216:217], v213 offset:0x3a00
	s_waitcnt lgkmcnt(8)
	v_mfma_f32_32x32x16_bf16 v[0:15], v[64:67], v[92:95], v[0:15]
	s_waitcnt lgkmcnt(6)
	v_mfma_f32_32x32x16_bf16 v[16:31], v[76:79], v[80:83], v[16:31]
	ds_read_b64_tr_b16 v[80:81], v213 offset:0x400
	ds_read_b64_tr_b16 v[82:83], v213 offset:0xc00
	s_waitcnt lgkmcnt(6)
	v_mfma_f32_32x32x16_bf16 v[16:31], v[72:75], v[84:87], v[16:31]
	ds_read_b64_tr_b16 v[84:85], v213 offset:0x1400
	ds_read_b64_tr_b16 v[86:87], v213 offset:0x1c00
	s_waitcnt lgkmcnt(6)
	v_mfma_f32_32x32x16_bf16 v[16:31], v[68:71], v[88:91], v[16:31]
	ds_read_b64_tr_b16 v[88:89], v213 offset:0x2400
	ds_read_b64_tr_b16 v[90:91], v213 offset:0x2c00
	ds_read_b64_tr_b16 v[92:93], v213 offset:0x3400
	ds_read_b64_tr_b16 v[94:95], v213 offset:0x3c00
	s_waitcnt lgkmcnt(8)
	v_mfma_f32_32x32x16_bf16 v[16:31], v[64:67], v[214:217], v[16:31]
	s_waitcnt lgkmcnt(6)
	v_mfma_f32_32x32x16_bf16 v[32:47], v[76:79], v[80:83], v[32:47]
	ds_read_b64_tr_b16 v[80:81], v213 offset:0x600
	ds_read_b64_tr_b16 v[82:83], v213 offset:0xe00
	s_waitcnt lgkmcnt(6)
	v_mfma_f32_32x32x16_bf16 v[32:47], v[72:75], v[84:87], v[32:47]
	ds_read_b64_tr_b16 v[84:85], v213 offset:0x1600
	ds_read_b64_tr_b16 v[86:87], v213 offset:0x1e00
	s_waitcnt lgkmcnt(6)
	v_mfma_f32_32x32x16_bf16 v[32:47], v[68:71], v[88:91], v[32:47]
	ds_read_b64_tr_b16 v[88:89], v213 offset:0x2600
	ds_read_b64_tr_b16 v[90:91], v213 offset:0x2e00
	ds_read_b64_tr_b16 v[214:215], v213 offset:0x3600
	ds_read_b64_tr_b16 v[216:217], v213 offset:0x3e00
	s_waitcnt lgkmcnt(8)
	v_mfma_f32_32x32x16_bf16 v[32:47], v[64:67], v[92:95], v[32:47]
	s_waitcnt lgkmcnt(6)
	v_mfma_f32_32x32x16_bf16 v[48:63], v[76:79], v[80:83], v[48:63]
	s_waitcnt lgkmcnt(4)
	v_mfma_f32_32x32x16_bf16 v[48:63], v[72:75], v[84:87], v[48:63]
	s_waitcnt lgkmcnt(2)
	v_mfma_f32_32x32x16_bf16 v[48:63], v[68:71], v[88:91], v[48:63]
	s_waitcnt lgkmcnt(0)
	v_mfma_f32_32x32x16_bf16 v[48:63], v[64:67], v[214:217], v[48:63]
.LBB0_424:
	s_or_b64 exec, exec, s[8:9]
	s_and_b32 s52, s0, 1
	s_lshl_b32 s8, s52, 14
	s_lshl_b32 s9, s52, 13
	s_add_i32 s9, s9, 0x14000
	v_add3_u32 v213, s8, v189, v155
	ds_read_b128 v[214:217], v213 offset:49152
	ds_read_b128 v[218:221], v213 offset:57344
	v_add3_u32 v213, s8, v190, v155
	ds_read_b128 v[232:235], v213 offset:49152
	ds_read_b128 v[236:239], v213 offset:57344
	v_add3_u32 v213, s8, v191, v155
	ds_read_b128 v[240:243], v213 offset:49152
	ds_read_b128 v[244:247], v213 offset:57344
	s_waitcnt lgkmcnt(4)
	v_mfma_f32_32x32x16_bf16 v[80:95], v[214:217], v[96:99], 0
	v_mfma_f32_32x32x16_bf16 v[64:79], v[218:221], v[96:99], 0
	v_add3_u32 v213, s8, v195, v155
	ds_read_b128 v[214:217], v213 offset:49152
	ds_read_b128 v[218:221], v213 offset:57344
	s_waitcnt lgkmcnt(4)
	v_mfma_f32_32x32x16_bf16 v[80:95], v[232:235], v[100:103], v[80:95]
	v_mfma_f32_32x32x16_bf16 v[64:79], v[236:239], v[100:103], v[64:79]
	v_add3_u32 v213, s8, v196, v155
	ds_read_b128 v[232:235], v213 offset:49152
	ds_read_b128 v[236:239], v213 offset:57344
	s_waitcnt lgkmcnt(4)
	v_mfma_f32_32x32x16_bf16 v[80:95], v[240:243], v[104:107], v[80:95]
	v_mfma_f32_32x32x16_bf16 v[64:79], v[244:247], v[104:107], v[64:79]
	v_add3_u32 v213, s8, v197, v155
	ds_read_b128 v[240:243], v213 offset:49152
	ds_read_b128 v[244:247], v213 offset:57344
	s_waitcnt lgkmcnt(4)
	v_mfma_f32_32x32x16_bf16 v[80:95], v[214:217], v[108:111], v[80:95]
	v_mfma_f32_32x32x16_bf16 v[64:79], v[218:221], v[108:111], v[64:79]
	v_add3_u32 v213, s8, v198, v155
	ds_read_b128 v[214:217], v213 offset:49152
	ds_read_b128 v[218:221], v213 offset:57344
	s_waitcnt lgkmcnt(4)
	v_mfma_f32_32x32x16_bf16 v[80:95], v[232:235], v[112:115], v[80:95]
	v_mfma_f32_32x32x16_bf16 v[64:79], v[236:239], v[112:115], v[64:79]
	v_add3_u32 v213, s8, v199, v155
	ds_read_b128 v[232:235], v213 offset:49152
	ds_read_b128 v[236:239], v213 offset:57344
	s_waitcnt lgkmcnt(4)
	v_mfma_f32_32x32x16_bf16 v[80:95], v[240:243], v[116:119], v[80:95]
	v_mfma_f32_32x32x16_bf16 v[64:79], v[244:247], v[116:119], v[64:79]
	v_add_u32_e32 v213, s9, v200
	ds_read_b128 v[240:243], v213
	ds_read_b128 v[244:247], v213 offset:4096
	v_add_u32_e32 v213, v175, v200
	ds_read_b128 v[248:251], v213
	s_waitcnt lgkmcnt(5)
	v_mfma_f32_32x32x16_bf16 v[80:95], v[214:217], v[120:123], v[80:95]
	v_mfma_f32_32x32x16_bf16 v[64:79], v[218:221], v[120:123], v[64:79]
	v_add_u32_e32 v213, s9, v201
	ds_read_b128 v[214:217], v213
	ds_read_b128 v[218:221], v213 offset:4096
	v_add_u32_e32 v213, v175, v201
	ds_read_b128 v[222:225], v213
	s_waitcnt lgkmcnt(6)
; __device__ __forceinline__ void partialSM(f32x16& p0, f32x16& p1, float& m_reg, float& mn, float& alpha, const float C, const float thr_raw) {
;   float pmax = p0[0];
; #pragma unroll
;   for (int r = 1; r < 16; ++r) pmax = fmaxf(pmax, p0[r]);
; #pragma unroll
;   for (int r = 0; r < 16; ++r) pmax = fmaxf(pmax, p1[r]);
;   { auto rr = __builtin_amdgcn_permlane32_swap(__float_as_uint(pmax), __float_as_uint(pmax), false, false);
;     pmax = fmaxf(__uint_as_float(rr[0]), __uint_as_float(rr[1])); }
;   if (__builtin_expect(__all(pmax - m_reg <= thr_raw), 1)) { mn = m_reg; alpha = 1.f; }
;   else { mn = fmaxf(m_reg, pmax); alpha = __builtin_amdgcn_exp2f((m_reg - mn) * C); m_reg = mn; }
;   const float mnC = -mn * C;
; #pragma unroll
;   for (int r = 0; r < 16; ++r) p0[r] = fmaf(p0[r], C, mnC);
; #pragma unroll
;   for (int r = 0; r < 16; ++r) p1[r] = fmaf(p1[r], C, mnC);
; #pragma unroll
;   for (int r = 0; r < 16; ++r) p0[r] = __builtin_amdgcn_exp2f(p0[r]);
; }
; template <int NQK, int NREG>
; __device__ __forceinline__ void qkt(f32x16& p0, f32x16& p1, const char* Ks, const char* KRs, const bf16x8* qr, const char* qrl, int r32, int hi) {
;   p0 = f32x16{}; p1 = f32x16{};
; #pragma unroll
;   for (int d0 = 0; d0 < 8; ++d0) { const int cb = (d0 * 16 + hi * 8) * 2;
;     bf16x8 b0 = *reinterpret_cast<const bf16x8*>(Ks + KSWZ(r32, cb));
;     bf16x8 b1 = *reinterpret_cast<const bf16x8*>(Ks + KSWZ(32 + r32, cb));
;     bf16x8 qq; if (d0 < NREG) qq = qr[d0 < NREG ? d0 : 0]; else qq = *reinterpret_cast<const bf16x8*>(qrl + KRSWZ(r32, (d0 - 4) * 2 + hi));
;     p0 = __builtin_amdgcn_mfma_f32_32x32x16_bf16(b0, qq, p0, 0, 0, 0);
;     p1 = __builtin_amdgcn_mfma_f32_32x32x16_bf16(b1, qq, p1, 0, 0, 0); }
;   if constexpr (NQK == 12) {
; #pragma unroll
;     for (int d0 = 0; d0 < 4; ++d0) { const int ch = d0 * 2 + hi;
;       bf16x8 b0 = *reinterpret_cast<const bf16x8*>(KRs + KRSWZ(r32, ch));
;       bf16x8 b1 = *reinterpret_cast<const bf16x8*>(KRs + KRSWZ(32 + r32, ch));
;       const bf16x8 qq = *reinterpret_cast<const bf16x8*>(qrl + 4096 + KRSWZ(r32, ch));
;       p0 = __builtin_amdgcn_mfma_f32_32x32x16_bf16(b0, qq, p0, 0, 0, 0);
;       p1 = __builtin_amdgcn_mfma_f32_32x32x16_bf16(b1, qq, p1, 0, 0, 0); }
;   }
; }
	v_mfma_f32_32x32x16_bf16 v[80:95], v[232:235], v[124:127], v[80:95]
	v_mfma_f32_32x32x16_bf16 v[64:79], v[236:239], v[124:127], v[64:79]
	v_add_u32_e32 v213, s9, v202
	ds_read_b128 v[232:235], v213
	ds_read_b128 v[236:239], v213 offset:4096
	v_add_u32_e32 v213, v175, v202
	ds_read_b128 v[226:229], v213
	s_waitcnt lgkmcnt(6)
	v_mfma_f32_32x32x16_bf16 v[80:95], v[240:243], v[248:251], v[80:95]
	v_mfma_f32_32x32x16_bf16 v[64:79], v[244:247], v[248:251], v[64:79]
	v_add_u32_e32 v213, s9, v203
	ds_read_b128 v[240:243], v213
	ds_read_b128 v[244:247], v213 offset:4096
	v_add_u32_e32 v213, v175, v203
	ds_read_b128 v[248:251], v213
	s_waitcnt lgkmcnt(6)
	v_mfma_f32_32x32x16_bf16 v[80:95], v[214:217], v[222:225], v[80:95]
	v_mfma_f32_32x32x16_bf16 v[64:79], v[218:221], v[222:225], v[64:79]
	s_waitcnt lgkmcnt(3)
	v_mfma_f32_32x32x16_bf16 v[80:95], v[232:235], v[226:229], v[80:95]
	v_mfma_f32_32x32x16_bf16 v[64:79], v[236:239], v[226:229], v[64:79]
	s_waitcnt lgkmcnt(0)
	v_mfma_f32_32x32x16_bf16 v[80:95], v[240:243], v[248:251], v[80:95]
	v_mfma_f32_32x32x16_bf16 v[64:79], v[244:247], v[248:251], v[64:79]
	s_setprio 0
	s_nop 10
	v_max_f32_e32 v213, v81, v81
	v_max_f32_e32 v230, v80, v80
	v_max_f32_e32 v213, v230, v213
	v_max3_f32 v213, v213, v82, v83
	v_max3_f32 v213, v213, v84, v85
	v_max3_f32 v213, v213, v86, v87
	v_max3_f32 v213, v213, v88, v89
	v_max3_f32 v213, v213, v90, v91
	v_max3_f32 v213, v213, v92, v93
	v_max3_f32 v213, v213, v94, v95
	v_max3_f32 v213, v213, v64, v65
	v_max3_f32 v213, v213, v66, v67
	v_max3_f32 v213, v213, v68, v69
	v_max3_f32 v213, v213, v70, v71
	v_max3_f32 v213, v213, v72, v73
	v_max3_f32 v213, v213, v74, v75
	v_max3_f32 v213, v213, v76, v77
	v_max3_f32 v213, v213, v78, v79
	v_mov_b32_e32 v214, v213
	s_nop 1
	v_permlane32_swap_b32_e32 v213, v214
	v_max_f32_e32 v214, v214, v214
	v_max_f32_e32 v213, v213, v213
	v_max_f32_e32 v213, v213, v214
	v_max_f32_e32 v214, v165, v165
	v_max_f32_e32 v214, v214, v213
	v_sub_f32_e32 v215, v213, v165
	v_sub_f32_e32 v213, v165, v214
	v_mul_f32_e32 v213, 0x3dd53b94, v213
	v_exp_f32_e32 v213, v213
	v_cmp_ge_f32_e32 vcc, s44, v215
	s_cmp_eq_u64 vcc, exec
	s_cselect_b64 s[8:9], -1, 0
	v_cndmask_b32_e64 v213, v213, 1.0, s[8:9]
	v_cmp_gt_f32_e32 vcc, 1.0, v213
	s_cbranch_vccz .LBB0_428
	s_and_saveexec_b64 s[18:19], s[4:5]
	ds_write_b32 v194, v213 offset:128
	s_or_b64 exec, exec, s[18:19]
	s_waitcnt lgkmcnt(0)
	v_add_u32_e32 v215, v174, v188
	ds_read_b128 v[216:219], v215 offset:224
	ds_read_b128 v[220:223], v215 offset:192
	ds_read_b128 v[224:227], v215 offset:160
	ds_read_b128 v[228:231], v215 offset:128
	s_waitcnt lgkmcnt(3)
	v_pk_mul_f32 v[12:13], v[12:13], v[216:217]
	s_waitcnt lgkmcnt(2)
	v_pk_mul_f32 v[8:9], v[8:9], v[220:221]
	s_waitcnt lgkmcnt(1)
	v_pk_mul_f32 v[4:5], v[4:5], v[224:225]
	v_pk_mul_f32 v[14:15], v[14:15], v[218:219]
	v_pk_mul_f32 v[10:11], v[10:11], v[222:223]
	v_pk_mul_f32 v[6:7], v[6:7], v[226:227]
	s_waitcnt lgkmcnt(0)
	v_pk_mul_f32 v[2:3], v[2:3], v[230:231]
	v_pk_mul_f32 v[0:1], v[0:1], v[228:229]
	v_pk_mul_f32 v[28:29], v[28:29], v[216:217]
	v_pk_mul_f32 v[24:25], v[24:25], v[220:221]
	v_pk_mul_f32 v[20:21], v[20:21], v[224:225]
	v_pk_mul_f32 v[30:31], v[30:31], v[218:219]
	v_pk_mul_f32 v[26:27], v[26:27], v[222:223]
	v_pk_mul_f32 v[22:23], v[22:23], v[226:227]
	v_pk_mul_f32 v[18:19], v[18:19], v[230:231]
	v_pk_mul_f32 v[16:17], v[16:17], v[228:229]
	v_pk_mul_f32 v[44:45], v[44:45], v[216:217]
	v_pk_mul_f32 v[40:41], v[40:41], v[220:221]
	v_pk_mul_f32 v[36:37], v[36:37], v[224:225]
	v_pk_mul_f32 v[46:47], v[46:47], v[218:219]
	v_pk_mul_f32 v[42:43], v[42:43], v[222:223]
	v_pk_mul_f32 v[38:39], v[38:39], v[226:227]
	v_pk_mul_f32 v[34:35], v[34:35], v[230:231]
	v_pk_mul_f32 v[32:33], v[32:33], v[228:229]
	v_pk_mul_f32 v[60:61], v[60:61], v[216:217]
	v_pk_mul_f32 v[56:57], v[56:57], v[220:221]
	v_pk_mul_f32 v[52:53], v[52:53], v[224:225]
	v_pk_mul_f32 v[62:63], v[62:63], v[218:219]
	v_pk_mul_f32 v[58:59], v[58:59], v[222:223]
	v_pk_mul_f32 v[54:55], v[54:55], v[226:227]
	v_pk_mul_f32 v[50:51], v[50:51], v[230:231]
	v_pk_mul_f32 v[48:49], v[48:49], v[228:229]
.LBB0_428:
	v_cndmask_b32_e64 v165, v214, v165, s[8:9]
	v_mul_f32_e32 v214, 0xbdd53b94, v165
	v_fmamk_f32 v80, v80, 0x3dd53b94, v214
	v_fmamk_f32 v81, v81, 0x3dd53b94, v214
	v_fmamk_f32 v82, v82, 0x3dd53b94, v214
	v_fmamk_f32 v83, v83, 0x3dd53b94, v214
	v_fmamk_f32 v84, v84, 0x3dd53b94, v214
	v_fmamk_f32 v85, v85, 0x3dd53b94, v214
	v_fmamk_f32 v86, v86, 0x3dd53b94, v214
	v_fmamk_f32 v87, v87, 0x3dd53b94, v214
	v_fmamk_f32 v88, v88, 0x3dd53b94, v214
	v_fmamk_f32 v89, v89, 0x3dd53b94, v214
	v_fmamk_f32 v90, v90, 0x3dd53b94, v214
	v_fmamk_f32 v91, v91, 0x3dd53b94, v214
	v_fmamk_f32 v92, v92, 0x3dd53b94, v214
	v_fmamk_f32 v93, v93, 0x3dd53b94, v214
	v_fmamk_f32 v94, v94, 0x3dd53b94, v214
	v_fmamk_f32 v95, v95, 0x3dd53b94, v214
	v_fmamk_f32 v64, v64, 0x3dd53b94, v214
	v_fmamk_f32 v65, v65, 0x3dd53b94, v214
	v_fmamk_f32 v66, v66, 0x3dd53b94, v214
	v_fmamk_f32 v67, v67, 0x3dd53b94, v214
	v_fmamk_f32 v68, v68, 0x3dd53b94, v214
	v_fmamk_f32 v69, v69, 0x3dd53b94, v214
	v_fmamk_f32 v70, v70, 0x3dd53b94, v214
	v_fmamk_f32 v71, v71, 0x3dd53b94, v214
	v_fmamk_f32 v72, v72, 0x3dd53b94, v214
	v_fmamk_f32 v73, v73, 0x3dd53b94, v214
	v_fmamk_f32 v74, v74, 0x3dd53b94, v214
	v_fmamk_f32 v75, v75, 0x3dd53b94, v214
	v_fmamk_f32 v76, v76, 0x3dd53b94, v214
	v_fmamk_f32 v77, v77, 0x3dd53b94, v214
	v_fmamk_f32 v78, v78, 0x3dd53b94, v214
	v_fmac_f32_e32 v214, 0x3dd53b94, v79
	v_exp_f32_e32 v79, v80
	v_exp_f32_e32 v215, v81
	v_exp_f32_e32 v82, v82
	v_exp_f32_e32 v83, v83
	v_exp_f32_e32 v84, v84
	v_exp_f32_e32 v216, v68
	v_add_f32_e32 v68, 0, v79
; #define SBAR() __builtin_amdgcn_sched_barrier(0)
; #define SWRITE1(b) do { *(bf16x8*)(V_lds + (b) * SHM_V + vst0) = vs0; *(bf16x8*)(V_lds + (b) * SHM_V + vst1) = vs1; const int kc = sc * 2; \
;     *(bf16x8*)(K_lds + (b) * SHM_K + KSWZ(sr, kc)) = ks0; *(bf16x8*)(K_lds + (b) * SHM_K + KSWZ(32 + sr, kc)) = ks1; \
;     if constexpr (NQK == 12) *(bf16x8*)(KR_lds + (b) * SHM_KR + KRSWZ(krr, krc)) = kr; } while (0)
; #define SWRITE1(b) do { *(bf16x8*)(V_lds + (b) * SHM_V + vst0) = vs0; *(bf16x8*)(V_lds + (b) * SHM_V + vst1) = vs1; const int kc = sc * 2; \
;     *(bf16x8*)(K_lds + (b) * SHM_K + KSWZ(sr, kc)) = ks0; *(bf16x8*)(K_lds + (b) * SHM_K + KSWZ(32 + sr, kc)) = ks1; \
;     if constexpr (NQK == 12) *(bf16x8*)(KR_lds + (b) * SHM_KR + KRSWZ(krr, krc)) = kr; } while (0)
; #define SWRITE1(b, vi) do { *(bf16x8*)(V_lds + (vi) * SHM_V + vst0) = vs0; *(bf16x8*)(V_lds + (vi) * SHM_V + vst1) = vs1; const int kc = sc * 2; \
;     *(bf16x8*)(K_lds + (b) * SHM_K + KSWZ(sr, kc)) = ks0; *(bf16x8*)(K_lds + (b) * SHM_K + KSWZ(32 + sr, kc)) = ks1; \
;     if constexpr (NQK == 12) *(bf16x8*)(KR_lds + (b) * SHM_KR + KRSWZ(krr, krc)) = kr; } while (0)
; __device__ __forceinline__ void finishSM(f32x16& p0, f32x16& p1, float alpha, float& l_reg, bf16x8& pa0, bf16x8& pa1, bf16x8& pa2, bf16x8& pa3) {
; #pragma unroll
;   for (int r = 0; r < 16; ++r) p1[r] = __builtin_amdgcn_exp2f(p1[r]);
;   float ps = 0;
; #pragma unroll
;   for (int r = 0; r < 16; ++r) ps += p0[r];
; #pragma unroll
;   for (int r = 0; r < 16; ++r) ps += p1[r];
;   { auto rr = __builtin_amdgcn_permlane32_swap(__float_as_uint(ps), __float_as_uint(ps), false, false);
;     ps = __uint_as_float(rr[0]) + __uint_as_float(rr[1]); }
;   l_reg = l_reg * alpha + ps;
;     ...
;   PK4(p0, 0, pa0); PK4(p0, 8, pa1); PK4(p1, 0, pa2); PK4(p1, 8, pa3);
;     ...
; }
; template <int NQK, int LDQ, int LDQR> ...
;     ...
;     finishSM(p0, p1, al, l_reg, pa0, pa1, pa2, pa3); SBAR();
;     if (grp == 0) pv_d0(o, vb0 + vcur * SHM_V, pa0, pa1, pa2, pa3);
;     if (j + 1 < NT) { SWRITE1(b ^ 1, vnext); if (j + 2 < NT) SLOAD1((j + 2) * KVBLK); }
	v_exp_f32_e32 v85, v85
	v_add_f32_e32 v68, v215, v68
	v_exp_f32_e32 v86, v86
	v_add_f32_e32 v68, v82, v68
	v_exp_f32_e32 v87, v87
	v_add_f32_e32 v68, v83, v68
	v_exp_f32_e32 v88, v88
	v_add_f32_e32 v68, v84, v68
	v_exp_f32_e32 v89, v89
	v_add_f32_e32 v68, v85, v68
	v_exp_f32_e32 v90, v90
	v_add_f32_e32 v68, v86, v68
	v_exp_f32_e32 v91, v91
	v_add_f32_e32 v68, v87, v68
	v_exp_f32_e32 v92, v92
	v_add_f32_e32 v68, v88, v68
	v_exp_f32_e32 v93, v93
	v_add_f32_e32 v68, v89, v68
	v_exp_f32_e32 v94, v94
	v_add_f32_e32 v68, v90, v68
	v_exp_f32_e32 v95, v95
	v_add_f32_e32 v68, v91, v68
	v_exp_f32_e32 v64, v64
	v_add_f32_e32 v68, v92, v68
	v_exp_f32_e32 v65, v65
	v_add_f32_e32 v68, v93, v68
	v_exp_f32_e32 v66, v66
	v_add_f32_e32 v68, v94, v68
	v_exp_f32_e32 v67, v67
	v_add_f32_e32 v68, v95, v68
	v_add_f32_e32 v68, v64, v68
	v_exp_f32_e32 v217, v69
	v_add_f32_e32 v68, v65, v68
	v_exp_f32_e32 v218, v70
	v_add_f32_e32 v68, v66, v68
	v_exp_f32_e32 v71, v71
	v_add_f32_e32 v68, v67, v68
	v_exp_f32_e32 v219, v72
	v_add_f32_e32 v68, v216, v68
	v_exp_f32_e32 v220, v73
	v_add_f32_e32 v68, v217, v68
	v_exp_f32_e32 v221, v74
	v_add_f32_e32 v68, v218, v68
	v_exp_f32_e32 v222, v75
	v_add_f32_e32 v68, v71, v68
	v_exp_f32_e32 v223, v76
	v_add_f32_e32 v68, v219, v68
	v_exp_f32_e32 v224, v77
	v_add_f32_e32 v68, v220, v68
	v_exp_f32_e32 v225, v78
	v_add_f32_e32 v68, v221, v68
	v_exp_f32_e32 v214, v214
	v_add_f32_e32 v68, v222, v68
	v_add_f32_e32 v68, v223, v68
	v_add_f32_e32 v68, v224, v68
	v_add_f32_e32 v68, v225, v68
	v_add_f32_e32 v80, v214, v68
	v_mov_b32_e32 v81, v80
	v_cvt_pk_bf16_f32 v76, v79, v215
	v_cvt_pk_bf16_f32 v77, v82, v83
	v_cvt_pk_bf16_f32 v78, v84, v85
	v_cvt_pk_bf16_f32 v79, v86, v87
	v_cvt_pk_bf16_f32 v72, v88, v89
	v_cvt_pk_bf16_f32 v73, v90, v91
	v_cvt_pk_bf16_f32 v74, v92, v93
	v_cvt_pk_bf16_f32 v75, v94, v95
	v_cvt_pk_bf16_f32 v68, v64, v65
	v_cvt_pk_bf16_f32 v69, v66, v67
	v_cvt_pk_bf16_f32 v70, v216, v217
	v_cvt_pk_bf16_f32 v71, v218, v71
	v_cvt_pk_bf16_f32 v64, v219, v220
	v_cvt_pk_bf16_f32 v65, v221, v222
	v_cvt_pk_bf16_f32 v66, v223, v224
	v_cvt_pk_bf16_f32 v67, v225, v214
	s_nop 1
	v_permlane32_swap_b32_e32 v80, v81
	v_permlane32_swap_b32_e32 v76, v78
	v_permlane32_swap_b32_e32 v77, v79
	v_permlane32_swap_b32_e32 v72, v74
	v_permlane32_swap_b32_e32 v73, v75
	v_permlane32_swap_b32_e32 v68, v70
	v_permlane32_swap_b32_e32 v69, v71
	v_permlane32_swap_b32_e32 v64, v66
	v_permlane32_swap_b32_e32 v65, v67
	s_setprio 1
	s_and_saveexec_b64 s[8:9], s[6:7]
	s_cbranch_execz .LBB0_430
	v_lshl_add_u32 v94, s51, 14, v183
	ds_read_b64_tr_b16 v[82:83], v94 offset:0
	ds_read_b64_tr_b16 v[84:85], v94 offset:0x800
	ds_read_b64_tr_b16 v[86:87], v94 offset:0x1000
	ds_read_b64_tr_b16 v[88:89], v94 offset:0x1800
	ds_read_b64_tr_b16 v[90:91], v94 offset:0x2000
	ds_read_b64_tr_b16 v[92:93], v94 offset:0x2800
	ds_read_b64_tr_b16 v[214:215], v94 offset:0x3000
	ds_read_b64_tr_b16 v[216:217], v94 offset:0x3800
	s_waitcnt lgkmcnt(6)
	v_mfma_f32_32x32x16_bf16 v[0:15], v[76:79], v[82:85], v[0:15]
	ds_read_b64_tr_b16 v[82:83], v94 offset:0x200
	ds_read_b64_tr_b16 v[84:85], v94 offset:0xa00
	s_waitcnt lgkmcnt(6)
	v_mfma_f32_32x32x16_bf16 v[0:15], v[72:75], v[86:89], v[0:15]
	ds_read_b64_tr_b16 v[86:87], v94 offset:0x1200
	ds_read_b64_tr_b16 v[88:89], v94 offset:0x1a00
	s_waitcnt lgkmcnt(6)
	v_mfma_f32_32x32x16_bf16 v[0:15], v[68:71], v[90:93], v[0:15]
	ds_read_b64_tr_b16 v[90:91], v94 offset:0x2200
	ds_read_b64_tr_b16 v[92:93], v94 offset:0x2a00
	ds_read_b64_tr_b16 v[218:219], v94 offset:0x3200
	ds_read_b64_tr_b16 v[220:221], v94 offset:0x3a00
	s_waitcnt lgkmcnt(8)
	v_mfma_f32_32x32x16_bf16 v[0:15], v[64:67], v[214:217], v[0:15]
	s_waitcnt lgkmcnt(6)
	v_mfma_f32_32x32x16_bf16 v[16:31], v[76:79], v[82:85], v[16:31]
	ds_read_b64_tr_b16 v[82:83], v94 offset:0x400
	ds_read_b64_tr_b16 v[84:85], v94 offset:0xc00
	s_waitcnt lgkmcnt(6)
	v_mfma_f32_32x32x16_bf16 v[16:31], v[72:75], v[86:89], v[16:31]
	ds_read_b64_tr_b16 v[86:87], v94 offset:0x1400
	ds_read_b64_tr_b16 v[88:89], v94 offset:0x1c00
	s_waitcnt lgkmcnt(6)
	v_mfma_f32_32x32x16_bf16 v[16:31], v[68:71], v[90:93], v[16:31]
	ds_read_b64_tr_b16 v[90:91], v94 offset:0x2400
	ds_read_b64_tr_b16 v[92:93], v94 offset:0x2c00
	ds_read_b64_tr_b16 v[214:215], v94 offset:0x3400
	ds_read_b64_tr_b16 v[216:217], v94 offset:0x3c00
	s_waitcnt lgkmcnt(8)
	v_mfma_f32_32x32x16_bf16 v[16:31], v[64:67], v[218:221], v[16:31]
	s_waitcnt lgkmcnt(6)
	v_mfma_f32_32x32x16_bf16 v[32:47], v[76:79], v[82:85], v[32:47]
	ds_read_b64_tr_b16 v[82:83], v94 offset:0x600
	ds_read_b64_tr_b16 v[84:85], v94 offset:0xe00
	s_waitcnt lgkmcnt(6)
	v_mfma_f32_32x32x16_bf16 v[32:47], v[72:75], v[86:89], v[32:47]
	ds_read_b64_tr_b16 v[86:87], v94 offset:0x1600
	ds_read_b64_tr_b16 v[88:89], v94 offset:0x1e00
	s_waitcnt lgkmcnt(6)
	v_mfma_f32_32x32x16_bf16 v[32:47], v[68:71], v[90:93], v[32:47]
	ds_read_b64_tr_b16 v[90:91], v94 offset:0x2600
	ds_read_b64_tr_b16 v[92:93], v94 offset:0x2e00
	ds_read_b64_tr_b16 v[218:219], v94 offset:0x3600
	ds_read_b64_tr_b16 v[220:221], v94 offset:0x3e00
	s_waitcnt lgkmcnt(8)
	v_mfma_f32_32x32x16_bf16 v[32:47], v[64:67], v[214:217], v[32:47]
	s_waitcnt lgkmcnt(6)
	v_mfma_f32_32x32x16_bf16 v[48:63], v[76:79], v[82:85], v[48:63]
	s_waitcnt lgkmcnt(4)
	v_mfma_f32_32x32x16_bf16 v[48:63], v[72:75], v[86:89], v[48:63]
	s_waitcnt lgkmcnt(2)
	v_mfma_f32_32x32x16_bf16 v[48:63], v[68:71], v[90:93], v[48:63]
	s_waitcnt lgkmcnt(0)
	v_mfma_f32_32x32x16_bf16 v[48:63], v[64:67], v[218:221], v[48:63]
.LBB0_430:
	s_or_b64 exec, exec, s[8:9]
	s_setprio 0
	s_cmp_eq_u32 s16, 0x3e0000
	s_cbranch_scc1 .LBB0_433
	s_lshl_b32 s8, s50, 14
	s_add_i32 s8, s8, 0
	v_add_u32_e32 v82, s8, v181
	s_waitcnt vmcnt(0)
	ds_write_b128 v82, v[128:131]
	v_add_u32_e32 v82, s8, v182
	s_xor_b32 s8, s52, 1
	s_lshl_b32 s9, s8, 14
	s_add_i32 s9, s9, 0
	ds_write_b128 v82, v[132:135]
	v_add_u32_e32 v82, s9, v184
	ds_write_b128 v82, v[136:139] offset:49152
	v_add_u32_e32 v82, s9, v185
	ds_write_b128 v82, v[144:147] offset:49152
	v_lshl_add_u32 v82, s8, 13, v186
	s_cmp_gt_u32 s0, 29
	ds_write_b128 v82, v[140:143]
	s_cbranch_scc1 .LBB0_433
	v_lshl_add_u64 v[82:83], v[170:171], 0, s[16:17]
	v_add_co_u32_e32 v84, vcc, 0x18300000, v82
	v_lshl_add_u64 v[86:87], v[168:169], 0, s[16:17]
	s_nop 0
	v_addc_co_u32_e32 v85, vcc, 0, v83, vcc
	v_add_co_u32_e32 v88, vcc, 0x18300000, v86
	s_nop 1
	v_addc_co_u32_e32 v89, vcc, 0, v87, vcc
	v_add_co_u32_e32 v82, vcc, 0x15300000, v82
	global_load_dwordx4 v[128:131], v[84:85], off
	global_load_dwordx4 v[132:135], v[88:89], off
	v_addc_co_u32_e32 v83, vcc, 0, v83, vcc
	v_add_co_u32_e32 v84, vcc, 0x15300000, v86
	s_nop 1
	v_addc_co_u32_e32 v85, vcc, 0, v87, vcc
	global_load_dwordx4 v[136:139], v[82:83], off
	global_load_dwordx4 v[144:147], v[84:85], off
	global_load_dwordx4 v[140:143], v[172:173], off

; #define SBAR() __builtin_amdgcn_sched_barrier(0)
; template <int D0> __device__ __forceinline__ void pv_one(f32x16& od, int vb, bf16x8 pa0, bf16x8 pa1, bf16x8 pa2, bf16x8 pa3) {
;   const s16x4 l0 = tr_read<v_rd_off(D0, 0, 0)>(vb), h0 = tr_read<v_rd_off(D0, 0, 1)>(vb), l1 = tr_read<v_rd_off(D0, 1, 0)>(vb), h1 = tr_read<v_rd_off(D0, 1, 1)>(vb);
;   const s16x4 l2 = tr_read<v_rd_off(D0, 2, 0)>(vb), h2 = tr_read<v_rd_off(D0, 2, 1)>(vb), l3 = tr_read<v_rd_off(D0, 3, 0)>(vb), h3 = tr_read<v_rd_off(D0, 3, 1)>(vb);
;   asm volatile("s_waitcnt lgkmcnt(0)" ::: "memory"); SBAR();
;     ...
;   od = __builtin_amdgcn_mfma_f32_32x32x16_bf16(pa0, PK(l0, h0), od, 0, 0, 0);
;   od = __builtin_amdgcn_mfma_f32_32x32x16_bf16(pa1, PK(l1, h1), od, 0, 0, 0);
;   od = __builtin_amdgcn_mfma_f32_32x32x16_bf16(pa2, PK(l2, h2), od, 0, 0, 0);
;   od = __builtin_amdgcn_mfma_f32_32x32x16_bf16(pa3, PK(l3, h3), od, 0, 0, 0);
;     ...
; }
; __device__ __forceinline__ void pv_d0(f32x16* o, int vb, bf16x8 pa0, bf16x8 pa1, bf16x8 pa2, bf16x8 pa3) {
;   pv_one<0>(o[0], vb, pa0, pa1, pa2, pa3); pv_one<1>(o[1], vb, pa0, pa1, pa2, pa3); pv_one<2>(o[2], vb, pa0, pa1, pa2, pa3); pv_one<3>(o[3], vb, pa0, pa1, pa2, pa3);
; template <int NQK, int LDQ, int LDQR> ...
;     ...
;   if (grp == 1) pv_d0(o, vb0 + vprev * SHM_V, pa0, pa1, pa2, pa3);
.LBB0_435:
	s_and_saveexec_b64 s[8:9], s[2:3]
	s_cbranch_execz .LBB0_437
	ds_read_b64_tr_b16 v[82:83], v204 offset:0
	ds_read_b64_tr_b16 v[84:85], v204 offset:0x800
	ds_read_b64_tr_b16 v[86:87], v204 offset:0x1000
	ds_read_b64_tr_b16 v[88:89], v204 offset:0x1800
	ds_read_b64_tr_b16 v[90:91], v204 offset:0x2000
	ds_read_b64_tr_b16 v[92:93], v204 offset:0x2800
	ds_read_b64_tr_b16 v[94:95], v204 offset:0x3000
	ds_read_b64_tr_b16 v[96:97], v204 offset:0x3800
	s_waitcnt lgkmcnt(6)
	v_mfma_f32_32x32x16_bf16 v[0:15], v[76:79], v[82:85], v[0:15]
	ds_read_b64_tr_b16 v[82:83], v204 offset:0x200
	ds_read_b64_tr_b16 v[84:85], v204 offset:0xa00
	s_waitcnt lgkmcnt(6)
	v_mfma_f32_32x32x16_bf16 v[0:15], v[72:75], v[86:89], v[0:15]
	ds_read_b64_tr_b16 v[86:87], v204 offset:0x1200
	ds_read_b64_tr_b16 v[88:89], v204 offset:0x1a00
	s_waitcnt lgkmcnt(6)
	v_mfma_f32_32x32x16_bf16 v[0:15], v[68:71], v[90:93], v[0:15]
	ds_read_b64_tr_b16 v[90:91], v204 offset:0x2200
	ds_read_b64_tr_b16 v[92:93], v204 offset:0x2a00
	ds_read_b64_tr_b16 v[98:99], v204 offset:0x3200
	ds_read_b64_tr_b16 v[100:101], v204 offset:0x3a00
	s_waitcnt lgkmcnt(8)
	v_mfma_f32_32x32x16_bf16 v[0:15], v[64:67], v[94:97], v[0:15]
	s_waitcnt lgkmcnt(6)
	v_mfma_f32_32x32x16_bf16 v[16:31], v[76:79], v[82:85], v[16:31]
	ds_read_b64_tr_b16 v[82:83], v204 offset:0x400
	ds_read_b64_tr_b16 v[84:85], v204 offset:0xc00
	s_waitcnt lgkmcnt(6)
	v_mfma_f32_32x32x16_bf16 v[16:31], v[72:75], v[86:89], v[16:31]
	ds_read_b64_tr_b16 v[86:87], v204 offset:0x1400
	ds_read_b64_tr_b16 v[88:89], v204 offset:0x1c00
	s_waitcnt lgkmcnt(6)
	v_mfma_f32_32x32x16_bf16 v[16:31], v[68:71], v[90:93], v[16:31]
	ds_read_b64_tr_b16 v[90:91], v204 offset:0x2400
	ds_read_b64_tr_b16 v[92:93], v204 offset:0x2c00
	ds_read_b64_tr_b16 v[94:95], v204 offset:0x3400
	ds_read_b64_tr_b16 v[96:97], v204 offset:0x3c00
	s_waitcnt lgkmcnt(8)
	v_mfma_f32_32x32x16_bf16 v[16:31], v[64:67], v[98:101], v[16:31]
	s_waitcnt lgkmcnt(6)
	v_mfma_f32_32x32x16_bf16 v[32:47], v[76:79], v[82:85], v[32:47]
	ds_read_b64_tr_b16 v[82:83], v204 offset:0x600
	ds_read_b64_tr_b16 v[84:85], v204 offset:0xe00
	s_waitcnt lgkmcnt(6)
	v_mfma_f32_32x32x16_bf16 v[32:47], v[72:75], v[86:89], v[32:47]
	ds_read_b64_tr_b16 v[86:87], v204 offset:0x1600
	ds_read_b64_tr_b16 v[88:89], v204 offset:0x1e00
	s_waitcnt lgkmcnt(6)
	v_mfma_f32_32x32x16_bf16 v[32:47], v[68:71], v[90:93], v[32:47]
	ds_read_b64_tr_b16 v[90:91], v204 offset:0x2600
	ds_read_b64_tr_b16 v[92:93], v204 offset:0x2e00
	ds_read_b64_tr_b16 v[98:99], v204 offset:0x3600
	ds_read_b64_tr_b16 v[100:101], v204 offset:0x3e00
	s_waitcnt lgkmcnt(8)
	v_mfma_f32_32x32x16_bf16 v[32:47], v[64:67], v[94:97], v[32:47]
	s_waitcnt lgkmcnt(6)
	v_mfma_f32_32x32x16_bf16 v[48:63], v[76:79], v[82:85], v[48:63]
	s_waitcnt lgkmcnt(4)
	v_mfma_f32_32x32x16_bf16 v[48:63], v[72:75], v[86:89], v[48:63]
	s_waitcnt lgkmcnt(2)
	v_mfma_f32_32x32x16_bf16 v[48:63], v[68:71], v[90:93], v[48:63]
	s_waitcnt lgkmcnt(0)
	v_mfma_f32_32x32x16_bf16 v[48:63], v[64:67], v[98:101], v[48:63]

; #define LAS __attribute__((address_space(3)))
; template <int NQK, int LDQ, int LDQR, int SD, int NREG> ...
;   const int tid = threadIdx.x, wid = tid >> 6, lane = tid & 63, r32 = lane & 31, hi = lane >> 5;
;   char* V_lds = lds + OFF_V; char* K_lds = lds + OFF_K; char* KR_lds = lds + OFF_KR;
;   float* ws = (float*)(lds + OFF_WS) + wid * 64; float* li_l = ws; float* al_l = ws + 32;
;   float m_reg = -1e30f, l_reg = 0;
; #pragma unroll
;   for (int d = 0; d < 4; ++d) o[d] = f32x16{};
;   bf16x8 qr[NREG]; char* qrl = lds + OFF_QR + wid * 8192;
;   { const bf16_t* Qw = Qb + (long)(wid * 32 + r32) * LDQ + hi * 8;
; #pragma unroll
;     for (int d0 = 0; d0 < NREG; ++d0) { qr[d0] = *reinterpret_cast<const bf16x8*>(Qw + d0 * 16); asm volatile("" : "+v"(qr[d0])); }
;     if constexpr (NREG == 4) {
; #pragma unroll
;       for (int d0 = 0; d0 < 4; ++d0) *reinterpret_cast<bf16x8*>(qrl + KRSWZ(r32, d0 * 2 + hi)) = *reinterpret_cast<const bf16x8*>(Qw + (4 + d0) * 16); }
;     if constexpr (NQK == 12) { const bf16_t* Qw2 = Qrb + (long)(wid * 32 + r32) * LDQR + hi * 8;
; #pragma unroll
;       for (int d0 = 0; d0 < 4; ++d0) *reinterpret_cast<bf16x8*>(qrl + 4096 + KRSWZ(r32, d0 * 2 + hi)) = *reinterpret_cast<const bf16x8*>(Qw2 + d0 * 16); } }
;   const int sr = tid >> 4, sc = (tid & 15) * 8, vst0 = v_st(sr, sc), vst1 = v_st(32 + sr, sc);
;   const unsigned soff = (unsigned)(sr * LDKV + sc);
;   const int krr = tid >> 3, krc = tid & 7;
;   const int vb0 = (int)(uintptr_t)(LAS char*)V_lds + v_rd_base(lane);
;   struct { bf16x8 vs0, vs1, ks0, ks1, kr; } sr_[SD];
; __global__ void __launch_bounds__(512, 2) fwd_megakernel(const Params p) {
;     ...
;     for (int u = bid; u < 256; u += G) {
;       const int h = u & 3, rb = u >> 2, b = rb >> 3; const size_t rowq = (size_t)rb * 256, rowk = (size_t)b * MEMT;
;       const float sc = 0.08838834764831845f; f32x16 o[4];
;       at::attn_core<8, 512, 64, 2, 8>(o, (const bf16_t*)(ws + O_XQ) + rowq * 512 + h * 128, nullptr, (const bf16_t*)(ws + O_XKV) + rowk * 1024 + h * 128, nullptr,
;                                 (const bf16_t*)(ws + O_XKV) + rowk * 1024 + 512 + h * 128, MEMT, sc * 1.4426950408889634f, 8.f / sc, (char*)shm);
;       at::store_o_bf16_lds(o, (bf16_t*)(ws + O_XO) + rowq * 512 + h * 128, 512, (char*)shm + at::OFF_QR + (tid >> 6) * 8192);
.LBB0_695:
	s_or_b64 exec, exec, s[0:1]
	s_cmp_gt_i32 s76, 6
	s_cselect_b64 s[0:1], -1, 0
	s_cmp_lt_i32 s77, 7
	s_cselect_b64 s[2:3], -1, 0
	s_cmpk_gt_i32 s14, 0xff
	s_cselect_b64 s[4:5], -1, 0
	s_or_b64 s[0:1], s[0:1], s[4:5]
	s_or_b64 s[0:1], s[0:1], s[2:3]
	s_and_b64 vcc, exec, s[0:1]
	s_waitcnt lgkmcnt(0)
	s_barrier
	s_cbranch_vccnz .LBB0_712
	v_and_b32_e32 v4, 48, v153
	v_lshrrev_b32_e32 v5, 3, v187
	v_and_or_b32 v4, v5, 8, v4
	v_and_b32_e32 v3, 0x78, v192
	v_lshrrev_b32_e32 v5, 5, v187
	v_lshrrev_b32_e32 v4, 1, v4
	v_bfe_u32 v6, v192, 5, 2
	v_bfe_u32 v7, v187, 4, 2
	v_or_b32_e32 v4, v4, v6
	v_and_or_b32 v5, v5, 4, v7
	v_lshlrev_b32_e32 v7, 1, v3
	v_lshlrev_b32_e32 v4, 9, v4
	v_lshlrev_b32_e32 v5, 6, v5
	v_and_b32_e32 v8, 48, v7
	v_add_u32_e32 v10, 32, v153
	v_or3_b32 v9, v4, v5, v8
	v_and_b32_e32 v4, 0x70, v10
	v_lshlrev_b32_e32 v11, 1, v10
	v_and_or_b32 v4, v11, 8, v4
	s_add_u32 s10, s74, 0x17300000
	v_lshrrev_b32_e32 v4, 1, v4
	s_addc_u32 s11, s75, 0
	v_or_b32_e32 v4, v4, v6
	s_add_u32 s15, s74, 0x1e300000
	v_lshlrev_b32_e32 v4, 9, v4
	s_addc_u32 s16, s75, 0
	v_and_b32_e32 v0, 0x3c0, v187
	s_add_i32 s0, 0, 0x14000
	v_or3_b32 v5, v4, v5, v8
	v_lshl_or_b32 v4, v153, 10, v3
	v_lshlrev_b32_e32 v3, 4, v187
	v_lshlrev_b32_e32 v11, 1, v187
	v_lshl_add_u32 v170, v0, 2, s0
	v_lshlrev_b32_e32 v0, 8, v187
	v_lshlrev_b32_e32 v2, 9, v152
	s_mov_b32 s0, 0x3c000
	v_and_b32_e32 v6, 0xc0, v3
	v_and_b32_e32 v8, 32, v11
	v_and_b32_e32 v12, 0x118, v192
	v_and_b32_e32 v1, 63, v187
	v_and_or_b32 v0, v0, s0, v2
	v_or3_b32 v6, v8, v6, v12
	v_lshlrev_b32_e32 v8, 8, v153
	v_and_b32_e32 v12, 0xf0, v187
	s_add_i32 s0, 0, 0x4000
	v_bitop3_b32 v13, v7, v8, v12 bitop3:0xde
	v_lshlrev_b32_e32 v8, 8, v10
	v_lshlrev_b32_e32 v172, 4, v154
	v_cmp_gt_u32_e64 s[2:3], 32, v1
	s_add_u32 s18, s74, 0x18300000
	v_lshlrev_b32_e32 v1, 7, v187
	v_bitop3_b32 v7, v7, v8, v12 bitop3:0xde
	v_lshlrev_b32_e32 v8, 8, v152
	v_and_b32_e32 v10, 0xf0, v3
	v_or_b32_e32 v14, 32, v172
	v_or_b32_e32 v15, 64, v172
	v_or_b32_e32 v16, 0x60, v172
	v_or_b32_e32 v17, 0x80, v172
	v_or_b32_e32 v18, 0xa0, v172
	v_or_b32_e32 v19, 0xc0, v172
	v_or_b32_e32 v20, 0xe0, v172
	v_add_u32_e32 v174, s0, v6
	s_addc_u32 s19, s75, 0
	v_and_b32_e32 v1, 0x1e000, v1
	s_add_i32 s0, 0, 0x14800
	v_add_u32_e32 v171, 0, v6
	v_bitop3_b32 v12, v172, v8, v10 bitop3:0xde
	v_bitop3_b32 v14, v14, v8, v10 bitop3:0xde
	v_bitop3_b32 v15, v15, v8, v10 bitop3:0xde
	v_bitop3_b32 v16, v16, v8, v10 bitop3:0xde
	v_bitop3_b32 v17, v17, v8, v10 bitop3:0xde
	v_bitop3_b32 v18, v18, v8, v10 bitop3:0xde
	v_bitop3_b32 v19, v19, v8, v10 bitop3:0xde
	v_bitop3_b32 v10, v20, v8, v10 bitop3:0xde
	v_add_u32_e32 v1, s0, v1
	v_lshrrev_b32_e32 v6, 1, v187
	v_bfe_u32 v20, v187, 3, 3
	s_movk_i32 s0, 0x1e0
	v_and_or_b32 v6, v6, s0, v20
	v_and_b32_e32 v21, 7, v187
	v_and_b32_e32 v11, 62, v11
	v_mov_b32_e32 v161, 0
	v_lshlrev_b32_e32 v2, 3, v154
	v_lshlrev_b32_e32 v6, 9, v6
	v_lshlrev_b32_e32 v8, 3, v21
	v_lshl_add_u32 v21, v21, 4, v1
	v_lshlrev_b32_e32 v20, 7, v20
	v_add_u32_e32 v1, v1, v11
	v_and_b32_e32 v3, 0x200, v3
	v_lshl_add_u32 v173, v152, 2, v170
	s_movk_i32 s17, 0x4000
	s_lshl_b32 s20, s14, 7
	s_lshl_b32 s21, s78, 7
	v_lshlrev_b32_e32 v162, 1, v0
	v_mov_b32_e32 v163, v161
	v_lshlrev_b32_e32 v164, 1, v2
	v_mov_b32_e32 v165, v161
	v_lshlrev_b32_e32 v166, 1, v4
	v_mov_b32_e32 v167, v161
	s_mov_b32 s22, 0x10000
	v_add_u32_e32 v175, 0, v9
	v_add_u32_e32 v176, 0, v5
	v_add_u32_e32 v177, 0, v13
	v_add_u32_e32 v178, 0, v7
	v_add_u32_e32 v179, 0, v12
	s_mov_b32 s23, 0x42b504f3
	s_mov_b32 s24, 0x20000
	s_mov_b32 s25, 0x30000
	s_mov_b32 s28, 0x50000
	s_mov_b32 s29, 0x40000
	s_mov_b32 s30, 0x60000
	s_mov_b32 s31, 0x70000
	v_lshlrev_b32_e32 v160, 1, v6
	v_lshlrev_b32_e32 v168, 1, v8
	v_add_u32_e32 v180, v1, v3
	v_add_u32_e32 v181, v21, v20
	s_movk_i32 s33, 0x2000
	s_movk_i32 s36, 0x6000
	v_add_u32_e32 v182, 0, v14
	v_add_u32_e32 v183, 0, v15
	v_add_u32_e32 v184, 0, v16
	v_add_u32_e32 v185, 0, v17
	v_add_u32_e32 v186, 0, v18
	v_add_u32_e32 v188, 0, v19
	v_add_u32_e32 v189, 0, v10
	v_mov_b32_e32 v190, 0xf149f2ca
	s_mov_b32 s37, s14
	s_branch .LBB0_698
